# v84 = v83 + packed f32 ops within 8 slots of an MFMA in LRU and sb split into scalar pairs (7 sites, bit-identical)
# speedup vs baseline: 1.0071x; 1.0015x over previous
.LBB0_226:
	s_or_b64 exec, exec, s[12:13]
	s_lshl_b32 s0, s5, 8
	s_and_b32 s0, s0, 0xf00
	ds_read_b128 v[64:67], v221
	ds_read_b128 v[68:71], v221 offset:64
	ds_read_b128 v[76:79], v221 offset:2304
	ds_read_b128 v[80:83], v221 offset:2368
	v_or_b32_e32 v101, v168, v122
	v_or_b32_e32 v116, 3, v101
	v_cmp_lt_u32_e64 s[28:29], v116, v100
	v_or_b32_e32 v102, 16, v100
	v_cmp_lt_u32_e64 s[12:13], v101, v102
	v_cmp_lt_u32_e64 s[14:15], v116, v102
	s_waitcnt lgkmcnt(3)
	v_mfma_f32_16x16x32_bf16 v[72:75], v[64:67], v[48:51], 0
	s_waitcnt lgkmcnt(1)
	v_mfma_f32_16x16x32_bf16 v[84:87], v[76:79], v[48:51], 0
	v_mfma_f32_16x16x32_bf16 v[88:91], v[76:79], v[52:55], 0
	v_mfma_f32_16x16x32_bf16 v[72:75], v[68:71], v[56:59], v[72:75]
	v_mfma_f32_16x16x32_bf16 v[64:67], v[64:67], v[52:55], 0
	s_waitcnt lgkmcnt(0)
	v_mfma_f32_16x16x32_bf16 v[76:79], v[80:83], v[56:59], v[84:87]
	s_nop 4
	v_mul_f32_e64 v92, |v75|, s51
	v_mfma_f32_16x16x32_bf16 v[80:83], v[80:83], v[60:63], v[88:91]
	v_max_f32_e32 v113, 0, v73
	v_max_f32_e32 v84, v72, v72
	s_nop 0
	v_mul_f32_e64 v88, |v73|, s51
	v_mfma_f32_16x16x32_bf16 v[68:71], v[68:71], v[60:63], v[64:67]
	v_exp_f32_e32 v87, v88
	v_max_f32_e32 v104, v76, v76
	v_mul_f32_e64 v110, |v79|, s51
	v_max_f32_e32 v89, v74, v74
	v_add_f32_e32 v87, 1.0, v87
	s_nop 2
	v_max_f32_e32 v97, v70, v70
	v_mul_f32_e64 v90, |v74|, s51
	v_max_f32_e32 v91, v75, v75
	v_max_f32_e32 v93, v68, v68
	v_mul_f32_e64 v94, |v68|, s51
	v_mul_f32_e64 v96, |v69|, s51
	v_mul_f32_e64 v98, |v70|, s51
	v_mul_f32_e64 v107, |v77|, s51
	v_max_f32_e32 v111, 0, v84
	v_max_f32_e32 v84, 0, v97
	v_max_f32_e32 v97, 0, v104
	v_exp_f32_e32 v104, v110
	v_log_f32_e32 v87, v87
	v_mul_f32_e64 v105, |v76|, s51
	v_max_f32_e32 v114, 0, v89
	v_exp_f32_e32 v89, v90
	v_max_f32_e32 v115, 0, v91
	v_exp_f32_e32 v90, v92
	v_max_f32_e32 v92, 0, v93
	v_exp_f32_e32 v91, v94
	v_exp_f32_e32 v93, v96
	v_exp_f32_e32 v94, v98
	v_exp_f32_e32 v98, v107
	v_exp_f32_e32 v96, v105
	v_fmac_f32_e32 v113, 0x3f317218, v87
	v_add_f32_e32 v87, 1.0, v104
	v_mul_f32_e64 v103, |v71|, s51
	v_add_f32_e32 v93, 1.0, v93
	v_add_f32_e32 v107, 1.0, v98
	v_log_f32_e32 v87, v87
	v_or_b32_e32 v85, 16, v101
	v_max_f32_e32 v88, 0, v69
	v_exp_f32_e32 v95, v103
	v_max_f32_e32 v103, 0, v77
	v_add_f32_e32 v106, 1.0, v96
	v_log_f32_e32 v96, v93
	v_log_f32_e32 v93, v107
	v_cmp_lt_u32_e32 vcc, v85, v100
	v_mul_f32_e64 v86, |v72|, s51
	v_mul_f32_e64 v109, |v78|, s51
	v_max_f32_e32 v104, 0, v79
	v_mul_f32_e64 v85, |v80|, s51
	v_exp_f32_e32 v112, v86
	v_max_f32_e32 v86, 0, v71
	v_exp_f32_e32 v99, v109
	v_exp_f32_e32 v85, v85
	v_fmac_f32_e32 v104, 0x3f317218, v87
	v_add_f32_e32 v89, 1.0, v89
	v_fmac_f32_e32 v103, 0x3f317218, v93
	v_max_f32_e32 v93, 0, v80
	v_mul_f32_e64 v87, |v81|, s51
	v_add_f32_e32 v91, 1.0, v91
	v_log_f32_e32 v89, v89
	v_exp_f32_e32 v87, v87
	v_log_f32_e32 v98, v91
	v_log_f32_e32 v91, v106
	v_add_f32_e32 v90, 1.0, v90
	v_add_f32_e32 v94, 1.0, v94
	v_add_f32_e32 v95, 1.0, v95
	v_add_f32_e32 v99, 1.0, v99
	v_add_f32_e32 v85, 1.0, v85
	v_log_f32_e32 v109, v90
	v_log_f32_e32 v90, v94
	v_log_f32_e32 v94, v95
	v_log_f32_e32 v95, v99
	v_log_f32_e32 v99, v85
	v_fmac_f32_e32 v114, 0x3f317218, v89
	v_max_f32_e32 v89, 0, v81
	v_add_f32_e32 v85, 1.0, v87
	v_mul_f32_e64 v87, |v82|, s51
	v_fmac_f32_e32 v97, 0x3f317218, v91
	v_exp_f32_e32 v91, v87
	v_cndmask_b32_e64 v106, 0, -v97, vcc
	v_log_f32_e32 v97, v85
	v_add_f32_e32 v105, 1.0, v112
	v_max_f32_e32 v87, 0, v82
	v_add_f32_e32 v85, 1.0, v91
	v_mul_f32_e64 v91, |v83|, s51
	v_log_f32_e32 v105, v105
	v_exp_f32_e32 v91, v91
	v_fmac_f32_e32 v115, 0x3f317218, v109
	v_or_b32_e32 v109, 1, v101
	v_or_b32_e32 v112, 2, v101
	v_fmac_f32_e32 v111, 0x3f317218, v105
	v_max_f32_e32 v107, 0, v78
	v_add_f32_e32 v91, 1.0, v91
	v_cmp_lt_u32_e64 s[36:37], v109, v100
	v_cmp_lt_u32_e64 s[26:27], v112, v100
	v_cndmask_b32_e64 v105, 0, -v111, s[10:11]
	v_fmac_f32_e32 v107, 0x3f317218, v95
	v_log_f32_e32 v95, v85
	v_log_f32_e32 v91, v91
	v_cndmask_b32_e64 v110, 0, -v113, s[36:37]
	v_or_b32_e32 v111, 19, v101
	v_cndmask_b32_e64 v113, 0, -v114, s[26:27]
	v_or_b32_e32 v114, 18, v101
	v_or_b32_e32 v108, 17, v101
	v_cmp_lt_u32_e64 s[30:31], v114, v100
	v_cmp_lt_u32_e64 s[34:35], v111, v100
	v_cndmask_b32_e64 v115, 0, -v115, s[28:29]
	v_cmp_lt_u32_e64 s[38:39], v108, v100
	v_cndmask_b32_e64 v107, 0, -v107, s[30:31]
	v_cndmask_b32_e64 v100, 0, -v104, s[34:35]
	v_max_f32_e32 v85, 0, v83
	v_cndmask_b32_e64 v103, 0, -v103, s[38:39]
	v_pk_fma_f32 v[92:93], v[98:99], s[62:63], v[92:93] op_sel_hi:[1,0,1]
	v_cmp_lt_u32_e64 s[18:19], v108, v102
	v_cmp_lt_u32_e64 s[20:21], v109, v102
	v_cmp_lt_u32_e64 s[16:17], v114, v102
	v_cmp_lt_u32_e64 s[22:23], v111, v102
	v_cmp_lt_u32_e64 s[24:25], v112, v102
	v_add_f32_e32 v98, v115, v113
	v_add_f32_e32 v102, v100, v107
	v_pk_fma_f32 v[86:87], v[94:95], s[62:63], v[86:87] op_sel_hi:[1,0,1]
	v_pk_fma_f32 v[84:85], v[90:91], s[62:63], v[84:85] op_sel_hi:[1,0,1]
	v_add_f32_e32 v99, v110, v98
	v_add_f32_e32 v103, v103, v102
	v_pk_fma_f32 v[88:89], v[96:97], s[62:63], v[88:89] op_sel_hi:[1,0,1]
	v_cndmask_b32_e64 v87, 0, -v87, s[16:17]
	v_cndmask_b32_e64 v86, 0, -v86, s[14:15]
	v_cndmask_b32_e64 v85, 0, -v85, s[22:23]
	v_cndmask_b32_e64 v84, 0, -v84, s[24:25]
	v_add_f32_e32 v101, v105, v99
	v_add_f32_e32 v105, v106, v103
	v_cndmask_b32_e64 v89, 0, -v89, s[18:19]
	v_cndmask_b32_e64 v88, 0, -v88, s[20:21]
	v_pk_add_f32 v[90:91], v[84:85], v[86:87]
	v_mov_b32_e32 v84, v101
	v_mov_b32_e32 v87, v101
	v_mov_b32_e32 v94, v105
	v_mov_b32_e32 v95, v105
	v_cndmask_b32_e64 v93, 0, -v93, s[10:11]
	v_cndmask_b32_e64 v92, 0, -v92, s[12:13]
	v_pk_add_f32 v[88:89], v[88:89], v[90:91]
	v_permlane16_swap_b32_e32 v84, v87
	v_permlane16_swap_b32_e32 v94, v95
	v_pk_add_f32 v[92:93], v[92:93], v[88:89]
	v_cndmask_b32_e64 v84, v84, v87, s[8:9]
	v_cndmask_b32_e64 v94, v94, v95, s[8:9]
	v_add_f32_e32 v108, v101, v84
	v_mov_b32_e32 v84, v92
	v_mov_b32_e32 v87, v92
	v_add_f32_e32 v106, v105, v94
	v_mov_b32_e32 v94, v93
	v_mov_b32_e32 v95, v93
	v_permlane16_swap_b32_e32 v84, v87
	s_nop 0
	v_permlane16_swap_b32_e32 v94, v95
	v_cndmask_b32_e64 v95, v94, v95, s[8:9]
	v_cndmask_b32_e64 v94, v84, v87, s[8:9]
	v_mov_b32_e32 v84, v108
	v_mov_b32_e32 v87, v108
	v_mov_b32_e32 v96, v106
	v_mov_b32_e32 v97, v106
	v_pk_add_f32 v[94:95], v[92:93], v[94:95]
	v_permlane32_swap_b32_e32 v84, v87
	v_permlane32_swap_b32_e32 v96, v97
	v_cndmask_b32_e64 v109, v84, v87, s[6:7]
	v_mov_b32_e32 v84, v94
	v_mov_b32_e32 v87, v94
	v_cndmask_b32_e64 v107, v96, v97, s[6:7]
	v_mov_b32_e32 v96, v95
	v_mov_b32_e32 v97, v95
	v_permlane32_swap_b32_e32 v84, v87
	s_nop 0
	v_permlane32_swap_b32_e32 v96, v97
	v_add_f32_e32 v104, v106, v107
	v_cndmask_b32_e64 v97, v96, v97, s[6:7]
	v_cndmask_b32_e64 v96, v84, v87, s[6:7]
	v_sub_f32_e32 v84, v106, v105
	v_add_f32_e32 v87, 0, v104
	v_sub_f32_e32 v106, v108, v101
	v_fmac_f32_e32 v87, v208, v106
	v_fmac_f32_e32 v87, v209, v109
	v_add_f32_e32 v72, v72, v87
	v_add_f32_e32 v73, v73, v87
	v_add_f32_e32 v72, v101, v72
	v_add_f32_e32 v73, v99, v73
	v_mul_f32_e32 v72, 0x3fb8aa3b, v72
	v_mul_f32_e32 v73, 0x3fb8aa3b, v73
	v_exp_f32_e32 v72, v72
	v_exp_f32_e32 v73, v73
	v_fma_f32 v84, v208, v84, 0
	v_fmac_f32_e32 v84, v209, v107
	v_cndmask_b32_e64 v99, 0, v72, s[10:11]
	v_cndmask_b32_e64 v101, 0, v73, s[36:37]
	v_add_f32_e32 v72, v78, v84
	v_add_f32_e32 v73, v74, v87
	v_add_f32_e32 v72, v102, v72
	v_add_f32_e32 v73, v98, v73
	v_mul_f32_e32 v72, 0x3fb8aa3b, v72
	v_mul_f32_e32 v73, 0x3fb8aa3b, v73
	v_exp_f32_e32 v72, v72
	v_exp_f32_e32 v73, v73
	v_add_f32_e32 v74, v79, v84
	v_pk_add_f32 v[106:107], v[94:95], v[96:97]
	v_cndmask_b32_e64 v78, 0, v72, s[30:31]
	v_cndmask_b32_e64 v79, 0, v73, s[26:27]
	v_pk_add_f32 v[72:73], v[94:95], v[92:93] neg_lo:[0,1] neg_hi:[0,1]
	v_add_f32_e32 v76, v76, v84
	v_fma_f32 v73, v208, v73, 0
	v_add_f32_e32 v77, v77, v84
	v_fmac_f32_e32 v73, v209, v97
	v_add_f32_e32 v84, 0, v107
	v_fmac_f32_e32 v84, v208, v72
	v_add_f32_e32 v72, v80, v73
	v_add_f32_e32 v80, v81, v73
	v_add_f32_e32 v80, v89, v80
	v_mul_f32_e32 v80, 0x3fb8aa3b, v80
	v_exp_f32_e32 v80, v80
	v_fmac_f32_e32 v84, v209, v96
	ds_read2_b64 v[64:67], v222 offset0:32 offset1:36
	v_add_f32_e32 v75, v75, v87
	v_add_f32_e32 v68, v68, v84
	v_add_f32_e32 v69, v69, v84
	v_cndmask_b32_e64 v87, 0, v80, s[18:19]
	v_add_f32_e32 v80, v82, v73
	v_add_f32_e32 v70, v70, v84
	v_add_f32_e32 v73, v83, v73
	v_add_f32_e32 v71, v71, v84
	v_add_f32_e32 v76, v105, v76
	v_add_f32_e32 v77, v103, v77
	v_add_f32_e32 v74, v100, v74
	v_add_f32_e32 v75, v115, v75
	v_add_f32_e32 v72, v93, v72
	v_add_f32_e32 v68, v92, v68
	v_add_f32_e32 v69, v88, v69
	v_add_f32_e32 v80, v91, v80
	v_add_f32_e32 v70, v90, v70
	v_add_f32_e32 v73, v85, v73
	v_add_f32_e32 v71, v86, v71
	v_mul_f32_e32 v76, 0x3fb8aa3b, v76
	v_mul_f32_e32 v77, 0x3fb8aa3b, v77
	v_mul_f32_e32 v74, 0x3fb8aa3b, v74
	v_mul_f32_e32 v75, 0x3fb8aa3b, v75
	v_mul_f32_e32 v72, 0x3fb8aa3b, v72
	v_mul_f32_e32 v68, 0x3fb8aa3b, v68
	v_mul_f32_e32 v69, 0x3fb8aa3b, v69
	v_mul_f32_e32 v80, 0x3fb8aa3b, v80
	v_mul_f32_e32 v70, 0x3fb8aa3b, v70
	v_mul_f32_e32 v73, 0x3fb8aa3b, v73
	v_mul_f32_e32 v71, 0x3fb8aa3b, v71
	v_exp_f32_e32 v76, v76
	v_exp_f32_e32 v77, v77
	v_exp_f32_e32 v74, v74
	v_exp_f32_e32 v75, v75
	v_exp_f32_e32 v72, v72
	v_exp_f32_e32 v68, v68
	v_exp_f32_e32 v69, v69
	v_exp_f32_e32 v80, v80
	v_exp_f32_e32 v70, v70
	v_exp_f32_e32 v73, v73
	v_exp_f32_e32 v71, v71
	v_cndmask_b32_e32 v76, 0, v76, vcc
	v_cndmask_b32_e64 v77, 0, v77, s[38:39]
	v_cndmask_b32_e64 v74, 0, v74, s[34:35]
	v_cndmask_b32_e64 v75, 0, v75, s[28:29]
	v_cndmask_b32_e64 v72, 0, v72, s[10:11]
	v_cndmask_b32_e64 v68, 0, v68, s[12:13]
	v_cndmask_b32_e64 v69, 0, v69, s[20:21]
	v_cndmask_b32_e64 v84, 0, v80, s[16:17]
	v_cndmask_b32_e64 v70, 0, v70, s[24:25]
	v_cndmask_b32_e64 v73, 0, v73, s[22:23]
	v_cndmask_b32_e64 v71, 0, v71, s[14:15]
	v_cvt_pk_bf16_f32 v80, v99, v101
	v_cvt_pk_bf16_f32 v81, v79, v75
	v_cvt_pk_bf16_f32 v82, v76, v77
	v_cvt_pk_bf16_f32 v83, v78, v74
	v_cvt_pk_bf16_f32 v96, v68, v69
	v_cvt_pk_bf16_f32 v97, v70, v71
	v_cvt_pk_bf16_f32 v98, v72, v87
	v_cvt_pk_bf16_f32 v99, v84, v73
	s_waitcnt lgkmcnt(0)
	v_mfma_f32_16x16x32_bf16 v[92:95], v[64:67], v[80:83], 0
	ds_read2_b64 v[100:103], v212 offset1:4
	s_add_i32 s14, s0, 0xffffff80
	s_cmp_eq_u32 s0, 0
	v_mfma_f32_16x16x32_bf16 v[76:79], v[64:67], v[96:99], 0
	ds_read2_b64 v[64:67], v210 offset1:4
	s_cselect_b64 s[12:13], -1, 0
	v_mov_b32_e32 v105, v107
	s_waitcnt lgkmcnt(0)
	v_mfma_f32_16x16x32_bf16 v[88:91], v[64:67], v[80:83], 0
	s_and_b64 s[0:1], s[12:13], exec
	s_cselect_b32 s22, 0, s14
	v_mfma_f32_16x16x32_bf16 v[72:75], v[64:67], v[96:99], 0
	ds_read2_b64 v[64:67], v211 offset1:4
	s_waitcnt lgkmcnt(0)
	v_mfma_f32_16x16x32_bf16 v[84:87], v[64:67], v[80:83], 0
	v_mfma_f32_16x16x32_bf16 v[68:71], v[64:67], v[96:99], 0
	v_add_f32_e32 v64, v108, v109
	v_mov_b32_e32 v65, v106
	v_add_f32_e32 v104, v64, v104
	v_add_f32_e32 v105, v65, v105
	v_mfma_f32_16x16x32_bf16 v[80:83], v[100:103], v[80:83], 0
	v_cmp_gt_f32_e32 vcc, s63, v104
	v_cmp_gt_f32_e64 s[0:1], s63, v105
	s_and_b64 s[0:1], vcc, s[0:1]
	v_mfma_f32_16x16x32_bf16 v[64:67], v[100:103], v[96:99], 0
	s_mov_b64 vcc, s[0:1]
	v_add_f32_e32 v170, 0, v104
	v_add_f32_e32 v171, 0, v105
	s_cmp_eq_u64 vcc, exec
	s_mov_b64 s[0:1], -1
	s_cbranch_scc1 .LBB0_232
	v_cmp_lt_i32_e32 vcc, s22, v168
	s_mov_b64 s[0:1], 0
	s_and_saveexec_b64 s[14:15], vcc
	s_cbranch_execz .LBB0_231
	s_and_b32 s0, s33, 0xf00
	v_add_u32_e32 v112, s0, v213
	s_mov_b64 s[16:17], 0
	v_mov_b32_e32 v113, v214
	v_mov_b32_e32 v114, v125
